# k48: k47 + the same branch-free cross-row prefix in the four prologue logf scans of each attention unit
# baseline (speedup 1.0000x reference)
; #define DPP_SHL(v, n) __builtin_bit_cast(float, __builtin_amdgcn_update_dpp(0, __builtin_bit_cast(int, (v)), 0x100 | (n), 0xF, 0xF, true))
; __device__ __forceinline__ float lane0(float v) { return __builtin_bit_cast(float, __builtin_amdgcn_readfirstlane(__builtin_bit_cast(int, v))); }
; #define ATT_GLD16(dst, ptr) asm volatile("global_load_dwordx4 %0, %1, off" : "=&v"(dst) : "v"(ptr) : "memory")
; __device__ __forceinline__ float suffix_incl(float v, int lane) {
;     v += DPP_SHL(v, 1); v += DPP_SHL(v, 2); v += DPP_SHL(v, 4); v += DPP_SHL(v, 8);
;     const float t1 = __builtin_bit_cast(float, __builtin_amdgcn_readlane(__builtin_bit_cast(int, v), 16)), t2 = __builtin_bit_cast(float, __builtin_amdgcn_readlane(__builtin_bit_cast(int, v), 32)),
;                 t3 = __builtin_bit_cast(float, __builtin_amdgcn_readlane(__builtin_bit_cast(int, v), 48));
;     const int row = lane >> 4;
;     const float add = (row == 0) ? (t1 + t2) + t3 : (row == 1) ? t2 + t3 : (row == 2) ? t3 : 0.f;
;     return v + add;
; __device__ __forceinline__ void attn_unit(const UnitDesc& u, LAS unsigned char* shm, float qkmax, float thresh) {
;     ...
;     { const int t2 = NT >= 2 ? NT - 2 : 0, t3 = NT >= 3 ? NT - 3 : 0, t4 = NT >= 4 ? NT - 4 : 0;
;       ATT_GLD16(kA, ksrc + (size_t)t2 * 64 * 512); ATT_GLD16(vA, vsrc + (size_t)t2 * 64 * 512);
;       ATT_GLD16(kB, ksrc + (size_t)t3 * 64 * 512); ATT_GLD16(vB, vsrc + (size_t)t3 * 64 * 512);
;       ATT_GLD16(kC, ksrc + (size_t)t4 * 64 * 512); ATT_GLD16(vC, vsrc + (size_t)t4 * 64 * 512); }
;     bf16x8 qr[4];
; #pragma unroll
;     for (int d0 = 0; d0 < 4; ++d0) qr[d0] = (bf16x8){0, 0, 0, 0, 0, 0, 0, 0};
;     if (active) { const bf16_t* Qw = u.Q + (size_t)(wid * 32 + r32) * 512;
; #pragma unroll
;         for (int d0 = 0; d0 < 4; ++d0) qr[d0] = *(const bf16x8*)(Qw + d0 * 16 + hi * 8); }
;     float carry = 0.f, Rown = 0.f, Rq0 = 0.f, inc4[4];
; #pragma unroll
;     for (int i = 0; i < 4; ++i) inc4[i] = suffix_incl(lfb[i], lane);
; #pragma unroll
;     for (int i = 0; i < 4; ++i) { if (i < nband) { const int jb = nband - 1 - i; const float R = carry + inc4[i] - lfb[i];
;         const float ro = __shfl(R, 32 * (wid & 1) + r32); if (jb == (wid >> 1)) Rown = ro;
;         if (jb == 0) Rq0 = __shfl(R, 0);
;         carry += lane0(inc4[i]); } }
.LBB0_734:
	s_lshl_b64 s[12:13], s[28:29], 16
	v_lshl_add_u64 v[188:189], v[106:107], 0, s[12:13]
	global_load_dwordx4 v[66:69], v[188:189], off
	v_lshl_add_u64 v[188:189], v[108:109], 0, s[12:13]
	global_load_dwordx4 v[74:77], v[188:189], off
	s_lshl_b64 s[8:9], s[8:9], 16
	v_lshl_add_u64 v[188:189], v[106:107], 0, s[8:9]
	global_load_dwordx4 v[70:73], v[188:189], off
	v_lshl_add_u64 v[188:189], v[108:109], 0, s[8:9]
	global_load_dwordx4 v[82:85], v[188:189], off
	s_lshl_b64 s[8:9], s[10:11], 16
	v_lshl_add_u64 v[188:189], v[106:107], 0, s[8:9]
	global_load_dwordx4 v[78:81], v[188:189], off
	v_lshl_add_u64 v[188:189], v[108:109], 0, s[8:9]
	global_load_dwordx4 v[86:89], v[188:189], off
	v_lshrrev_b32_e32 v0, 4, v137
	v_cmp_ne_u32_e64 s[8:9], 1, v0
	v_cmp_eq_u32_e64 s[10:11], 2, v0
	s_waitcnt vmcnt(15)
	v_add_f32_dpp v0, v14, v14 row_shl:1 row_mask:0xf bank_mask:0xf bound_ctrl:1
	v_cmp_lt_u32_e64 s[6:7], 15, v137
	s_nop 0
	v_add_f32_dpp v0, v0, v0 row_shl:2 row_mask:0xf bank_mask:0xf bound_ctrl:1
	s_nop 1
	v_add_f32_dpp v0, v0, v0 row_shl:4 row_mask:0xf bank_mask:0xf bound_ctrl:1
	s_nop 1
	v_add_f32_dpp v0, v0, v0 row_shl:8 row_mask:0xf bank_mask:0xf bound_ctrl:1
	s_nop 0
	v_readlane_b32 s28, v0, 16
	v_readlane_b32 s70, v0, 32
	v_readlane_b32 s69, v0, 48
	s_nop 0
	v_mul_f32_e32 v11, s70, v192
	v_fmac_f32_e32 v11, s28, v191
	v_fmac_f32_e32 v11, s69, v193
	s_waitcnt vmcnt(14)
	v_add_f32_dpp v15, v140, v140 row_shl:1 row_mask:0xf bank_mask:0xf bound_ctrl:1
	s_nop 1
	v_add_f32_dpp v15, v15, v15 row_shl:2 row_mask:0xf bank_mask:0xf bound_ctrl:1
	s_nop 1
	v_add_f32_dpp v15, v15, v15 row_shl:4 row_mask:0xf bank_mask:0xf bound_ctrl:1
	s_nop 1
	v_add_f32_dpp v15, v15, v15 row_shl:8 row_mask:0xf bank_mask:0xf bound_ctrl:1
	s_nop 0
	v_readlane_b32 s28, v15, 16
	v_readlane_b32 s70, v15, 32
	v_readlane_b32 s69, v15, 48
	s_nop 0
	v_mul_f32_e32 v16, s70, v192
	v_fmac_f32_e32 v16, s28, v191
	v_fmac_f32_e32 v16, s69, v193
	s_waitcnt vmcnt(13)
	v_add_f32_dpp v17, v141, v141 row_shl:1 row_mask:0xf bank_mask:0xf bound_ctrl:1
	s_nop 1
	v_add_f32_dpp v17, v17, v17 row_shl:2 row_mask:0xf bank_mask:0xf bound_ctrl:1
	s_nop 1
	v_add_f32_dpp v17, v17, v17 row_shl:4 row_mask:0xf bank_mask:0xf bound_ctrl:1
	s_nop 1
	v_add_f32_dpp v17, v17, v17 row_shl:8 row_mask:0xf bank_mask:0xf bound_ctrl:1
	s_nop 0
	v_readlane_b32 s28, v17, 16
	v_readlane_b32 s70, v17, 32
	v_readlane_b32 s69, v17, 48
	s_nop 0
	v_mul_f32_e32 v18, s70, v192
	v_fmac_f32_e32 v18, s28, v191
	v_fmac_f32_e32 v18, s69, v193
	s_waitcnt vmcnt(12)
	v_add_f32_dpp v19, v139, v139 row_shl:1 row_mask:0xf bank_mask:0xf bound_ctrl:1
	s_nop 1
	v_add_f32_dpp v19, v19, v19 row_shl:2 row_mask:0xf bank_mask:0xf bound_ctrl:1
	s_nop 1
	v_add_f32_dpp v19, v19, v19 row_shl:4 row_mask:0xf bank_mask:0xf bound_ctrl:1
	s_nop 1
	v_add_f32_dpp v19, v19, v19 row_shl:8 row_mask:0xf bank_mask:0xf bound_ctrl:1
	s_nop 0
	v_readlane_b32 s28, v19, 16
	v_readlane_b32 s70, v19, 32
	v_readlane_b32 s69, v19, 48
	s_nop 0
	v_mul_f32_e32 v20, s70, v192
	v_fmac_f32_e32 v20, s28, v191
	v_fmac_f32_e32 v20, s69, v193
	v_add_f32_e32 v0, v0, v11
	v_and_or_b32 v11, s49, 32, v135
	v_add_f32_e32 v21, 0, v0
	v_or_b32_e32 v11, v128, v11
	v_sub_f32_e32 v23, v21, v14
	v_lshlrev_b32_e32 v22, 2, v11
	ds_bpermute_b32 v21, v22, v23
	s_lshr_b32 s28, s53, 6
	s_add_i32 s12, s28, -1
	s_cmp_lg_u32 s12, 0
	v_mov_b32_e32 v11, 0
	s_cbranch_scc1 .LBB0_768
	ds_bpermute_b32 v11, v132, v23
